# mixer-C epilogue: 16 row-per-lane dwordx2 stores -> 8 dwordx4 after v_permlane32_swap of adjacent 8-wide groups (same bytes, same addresses)
# speedup vs baseline: 1.0065x; 1.0008x over previous
; __device__ __forceinline__ unsigned pk_bf16(float lo, float hi) { return pg8::cvt_pk_bf16(lo, hi); }
; __device__ __forceinline__ float sq2(unsigned w) { const float a = bf_lo(w), b = bf_hi(w); return a * a + b * b; }
; __device__ __forceinline__ void attn_c_unit(LAS unsigned char* lds, const bf16_t* proj, const bf16_t* vt, bf16_t* obuf, int b, int hk, int blk, float mref, unsigned long long* sg) {
;     ...
;     l0 += __shfl_xor(l0, 32); l1 += __shfl_xor(l1, 32);
;     const float inv0 = 1.f / l0, inv1 = 1.f / l1;
;     bf16_t* og = obuf + (tokbase + qpos) * DM + ocol + 4 * h;
;     float qs0 = 0.f, qs1 = 0.f;
; #pragma unroll
;     for (int g = 0; g < 4; ++g) {
;         u32x2 a, c;
;         a.x = pk_bf16(o00[4 * g] * inv0, o00[4 * g + 1] * inv0); a.y = pk_bf16(o00[4 * g + 2] * inv0, o00[4 * g + 3] * inv0);
;         c.x = pk_bf16(o01[4 * g] * inv0, o01[4 * g + 1] * inv0); c.y = pk_bf16(o01[4 * g + 2] * inv0, o01[4 * g + 3] * inv0);
;         *(u32x2*)(og + 8 * g) = a; *(u32x2*)(og + 32 + 8 * g) = c;
;         qs0 += sq2(a.x) + sq2(a.y) + sq2(c.x) + sq2(c.y);
;         a.x = pk_bf16(o10[4 * g] * inv1, o10[4 * g + 1] * inv1); a.y = pk_bf16(o10[4 * g + 2] * inv1, o10[4 * g + 3] * inv1);
;         c.x = pk_bf16(o11[4 * g] * inv1, o11[4 * g + 1] * inv1); c.y = pk_bf16(o11[4 * g + 2] * inv1, o11[4 * g + 3] * inv1);
;         *(u32x2*)(og + (size_t)32 * DM + 8 * g) = a; *(u32x2*)(og + (size_t)32 * DM + 32 + 8 * g) = c;
;         qs1 += sq2(a.x) + sq2(a.y) + sq2(c.x) + sq2(c.y);
.LBB0_215:
	v_and_b32_e32 v65, 64, v221
	v_xor_b32_e32 v64, 32, v221
	v_add_u32_e32 v65, 64, v65
	v_cmp_lt_i32_e32 vcc, v64, v65
	v_lshlrev_b32_e32 v128, 3, v196
	s_nop 0
	v_cndmask_b32_e32 v64, v221, v64, vcc
	v_lshlrev_b32_e32 v65, 2, v64
	ds_bpermute_b32 v64, v65, v190
	ds_bpermute_b32 v66, v65, v191
	s_waitcnt lgkmcnt(1)
	v_add_f32_e32 v64, v190, v64
	s_waitcnt lgkmcnt(0)
	v_add_f32_e32 v67, v191, v66
	v_div_scale_f32 v66, s[14:15], v64, v64, 1.0
	v_rcp_f32_e32 v68, v66
	s_nop 0
	v_fma_f32 v69, -v66, v68, 1.0
	v_fmac_f32_e32 v68, v69, v68
	v_div_scale_f32 v69, vcc, 1.0, v64, 1.0
	v_mul_f32_e32 v70, v69, v68
	v_fma_f32 v71, -v66, v70, v69
	v_fmac_f32_e32 v70, v71, v68
	v_fma_f32 v66, -v66, v70, v69
	v_div_fmas_f32 v66, v66, v68, v70
	v_div_fixup_f32 v66, v66, v64, 1.0
	v_div_scale_f32 v64, s[14:15], v67, v67, 1.0
	v_rcp_f32_e32 v68, v64
	v_pk_mul_f32 v[32:33], v[32:33], v[66:67] op_sel_hi:[1,0]
	v_pk_mul_f32 v[34:35], v[34:35], v[66:67] op_sel_hi:[1,0]
	v_cvt_pk_bf16_f32 v32, v32, v33
	v_fma_f32 v69, -v64, v68, 1.0
	v_fmac_f32_e32 v68, v69, v68
	v_div_scale_f32 v69, vcc, 1.0, v67, 1.0
	v_mul_f32_e32 v70, v69, v68
	v_fma_f32 v71, -v64, v70, v69
	v_fmac_f32_e32 v70, v71, v68
	v_fma_f32 v64, -v64, v70, v69
	v_div_fmas_f32 v64, v64, v68, v70
	v_lshlrev_b64 v[68:69], 12, v[184:185]
	v_lshl_add_u64 v[68:69], s[88:89], 0, v[68:69]
	v_lshl_add_u64 v[68:69], s[12:13], 1, v[68:69]
	v_lshl_add_u64 v[68:69], v[68:69], 0, v[128:129]
	v_cvt_pk_bf16_f32 v33, v34, v35
	v_pk_mul_f32 v[34:35], v[48:49], v[66:67] op_sel_hi:[1,0]
	v_pk_mul_f32 v[48:49], v[50:51], v[66:67] op_sel_hi:[1,0]
	v_cvt_pk_bf16_f32 v34, v34, v35
	v_cvt_pk_bf16_f32 v35, v48, v49
	v_mov_b32_e32 v72, v32
	v_mov_b32_e32 v73, v33
	v_mov_b32_e32 v104, v68
	v_mov_b32_e32 v105, v69
	v_mov_b32_e32 v80, v34
	v_mov_b32_e32 v81, v35
	v_lshlrev_b32_e32 v48, 16, v32
	v_and_b32_e32 v32, 0xffff0000, v32
	v_mul_f32_e32 v32, v32, v32
	v_fmac_f32_e32 v32, v48, v48
	v_lshlrev_b32_e32 v48, 16, v33
	v_and_b32_e32 v33, 0xffff0000, v33
	v_mul_f32_e32 v33, v33, v33
	v_fmac_f32_e32 v33, v48, v48
	v_add_f32_e32 v32, v32, v33
	v_lshlrev_b32_e32 v33, 16, v34
	v_and_b32_e32 v34, 0xffff0000, v34
	v_mul_f32_e32 v34, v34, v34
	v_fmac_f32_e32 v34, v33, v33
	v_add_f32_e32 v32, v34, v32
	v_and_b32_e32 v34, 0xffff0000, v35
	v_div_fixup_f32 v64, v64, v67, 1.0
	v_lshlrev_b32_e32 v33, 16, v35
	v_mul_f32_e32 v34, v34, v34
	v_fmac_f32_e32 v34, v33, v33
	v_pk_mul_f32 v[0:1], v[0:1], v[64:65] op_sel_hi:[1,0]
	v_add_f32_e32 v34, v34, v32
	v_cvt_pk_bf16_f32 v32, v0, v1
	v_pk_mul_f32 v[0:1], v[2:3], v[64:65] op_sel_hi:[1,0]
	s_mov_b32 s12, 0x20000
	v_cvt_pk_bf16_f32 v33, v0, v1
	v_pk_mul_f32 v[0:1], v[16:17], v[64:65] op_sel_hi:[1,0]
	v_and_b32_e32 v17, 0xffff0000, v32
	v_cvt_pk_bf16_f32 v2, v0, v1
	v_pk_mul_f32 v[0:1], v[18:19], v[64:65] op_sel_hi:[1,0]
	v_lshlrev_b32_e32 v16, 16, v32
	v_mul_f32_e32 v17, v17, v17
	v_and_b32_e32 v18, 0xffff0000, v33
	v_cvt_pk_bf16_f32 v3, v0, v1
	v_add_co_u32_e32 v0, vcc, s12, v68
	v_fmac_f32_e32 v17, v16, v16
	v_lshlrev_b32_e32 v16, 16, v33
	v_mul_f32_e32 v18, v18, v18
	v_addc_co_u32_e32 v1, vcc, 0, v69, vcc
	v_fmac_f32_e32 v18, v16, v16
	v_mov_b32_e32 v88, v32
	v_mov_b32_e32 v89, v33
	v_mov_b32_e32 v106, v0
	v_mov_b32_e32 v107, v1
	v_mov_b32_e32 v96, v2
	v_mov_b32_e32 v97, v3
	v_add_f32_e32 v16, v17, v18
	v_lshlrev_b32_e32 v17, 16, v2
	v_and_b32_e32 v2, 0xffff0000, v2
	v_mul_f32_e32 v2, v2, v2
	v_fmac_f32_e32 v2, v17, v17
	v_add_f32_e32 v2, v2, v16
	v_lshlrev_b32_e32 v16, 16, v3
	v_and_b32_e32 v3, 0xffff0000, v3
	v_mul_f32_e32 v3, v3, v3
	v_fmac_f32_e32 v3, v16, v16
	v_add_f32_e32 v32, v3, v2
	v_pk_mul_f32 v[2:3], v[36:37], v[66:67] op_sel_hi:[1,0]
	v_pk_mul_f32 v[16:17], v[38:39], v[66:67] op_sel_hi:[1,0]
	v_cvt_pk_bf16_f32 v2, v2, v3
	v_cvt_pk_bf16_f32 v3, v16, v17
	v_pk_mul_f32 v[16:17], v[52:53], v[66:67] op_sel_hi:[1,0]
	v_pk_mul_f32 v[18:19], v[54:55], v[66:67] op_sel_hi:[1,0]
	v_cvt_pk_bf16_f32 v16, v16, v17
	v_cvt_pk_bf16_f32 v17, v18, v19
	v_mov_b32_e32 v74, v2
	v_mov_b32_e32 v75, v3
	v_mov_b32_e32 v82, v16
	v_mov_b32_e32 v83, v17
	v_lshlrev_b32_e32 v18, 16, v2
	v_and_b32_e32 v2, 0xffff0000, v2
	v_mul_f32_e32 v2, v2, v2
	v_fmac_f32_e32 v2, v18, v18
	v_lshlrev_b32_e32 v18, 16, v3
	v_and_b32_e32 v3, 0xffff0000, v3
	v_mul_f32_e32 v3, v3, v3
	v_fmac_f32_e32 v3, v18, v18
	v_add_f32_e32 v2, v2, v3
	v_lshlrev_b32_e32 v3, 16, v16
	v_and_b32_e32 v16, 0xffff0000, v16
	v_mul_f32_e32 v16, v16, v16
	v_fmac_f32_e32 v16, v3, v3
	v_add_f32_e32 v2, v16, v2
	v_and_b32_e32 v16, 0xffff0000, v17
	v_lshlrev_b32_e32 v3, 16, v17
	v_mul_f32_e32 v16, v16, v16
	v_fmac_f32_e32 v16, v3, v3
	v_add_f32_e32 v2, v16, v2
	v_add_f32_e32 v16, v34, v2
	v_pk_mul_f32 v[2:3], v[4:5], v[64:65] op_sel_hi:[1,0]
	v_pk_mul_f32 v[4:5], v[6:7], v[64:65] op_sel_hi:[1,0]
	v_cvt_pk_bf16_f32 v2, v2, v3
	v_cvt_pk_bf16_f32 v3, v4, v5
	v_pk_mul_f32 v[4:5], v[20:21], v[64:65] op_sel_hi:[1,0]
	v_pk_mul_f32 v[6:7], v[22:23], v[64:65] op_sel_hi:[1,0]
	v_cvt_pk_bf16_f32 v4, v4, v5
	v_cvt_pk_bf16_f32 v5, v6, v7
	v_mov_b32_e32 v90, v2
	v_mov_b32_e32 v91, v3
	v_mov_b32_e32 v98, v4
	v_mov_b32_e32 v99, v5
	v_lshlrev_b32_e32 v6, 16, v2
	v_and_b32_e32 v2, 0xffff0000, v2
	v_mul_f32_e32 v2, v2, v2
	v_fmac_f32_e32 v2, v6, v6
	v_lshlrev_b32_e32 v6, 16, v3
	v_and_b32_e32 v3, 0xffff0000, v3
	v_mul_f32_e32 v3, v3, v3
	v_fmac_f32_e32 v3, v6, v6
	v_add_f32_e32 v2, v2, v3
	v_lshlrev_b32_e32 v3, 16, v4
	v_and_b32_e32 v4, 0xffff0000, v4
	v_mul_f32_e32 v4, v4, v4
	v_fmac_f32_e32 v4, v3, v3
	v_add_f32_e32 v2, v4, v2
	v_and_b32_e32 v4, 0xffff0000, v5
	v_lshlrev_b32_e32 v3, 16, v5
	v_mul_f32_e32 v4, v4, v4
	v_fmac_f32_e32 v4, v3, v3
	v_add_f32_e32 v2, v4, v2
; __device__ __forceinline__ unsigned pk_bf16(float lo, float hi) { return pg8::cvt_pk_bf16(lo, hi); }
; __device__ __forceinline__ float sq2(unsigned w) { const float a = bf_lo(w), b = bf_hi(w); return a * a + b * b; }
; __device__ __forceinline__ void attn_c_unit(LAS unsigned char* lds, const bf16_t* proj, const bf16_t* vt, bf16_t* obuf, int b, int hk, int blk, float mref, unsigned long long* sg) {
;     ...
;     for (int g = 0; g < 4; ++g) {
;         u32x2 a, c;
;         a.x = pk_bf16(o00[4 * g] * inv0, o00[4 * g + 1] * inv0); a.y = pk_bf16(o00[4 * g + 2] * inv0, o00[4 * g + 3] * inv0);
;         c.x = pk_bf16(o01[4 * g] * inv0, o01[4 * g + 1] * inv0); c.y = pk_bf16(o01[4 * g + 2] * inv0, o01[4 * g + 3] * inv0);
;         *(u32x2*)(og + 8 * g) = a; *(u32x2*)(og + 32 + 8 * g) = c;
;         qs0 += sq2(a.x) + sq2(a.y) + sq2(c.x) + sq2(c.y);
;         a.x = pk_bf16(o10[4 * g] * inv1, o10[4 * g + 1] * inv1); a.y = pk_bf16(o10[4 * g + 2] * inv1, o10[4 * g + 3] * inv1);
;         c.x = pk_bf16(o11[4 * g] * inv1, o11[4 * g + 1] * inv1); c.y = pk_bf16(o11[4 * g + 2] * inv1, o11[4 * g + 3] * inv1);
;         *(u32x2*)(og + (size_t)32 * DM + 8 * g) = a; *(u32x2*)(og + (size_t)32 * DM + 32 + 8 * g) = c;
;         qs1 += sq2(a.x) + sq2(a.y) + sq2(c.x) + sq2(c.y);
;     }
;     qs0 += __shfl_xor(qs0, 32); qs1 += __shfl_xor(qs1, 32);
;     if (h == 0) { atomicAdd(sg + tokbase + qpos, (unsigned long long)(qs0 * 16777216.f)); atomicAdd(sg + tokbase + qpos + 32, (unsigned long long)(qs1 * 16777216.f)); }
	v_add_f32_e32 v17, v32, v2
	v_pk_mul_f32 v[2:3], v[40:41], v[66:67] op_sel_hi:[1,0]
	v_pk_mul_f32 v[4:5], v[42:43], v[66:67] op_sel_hi:[1,0]
	v_cvt_pk_bf16_f32 v2, v2, v3
	v_cvt_pk_bf16_f32 v3, v4, v5
	v_pk_mul_f32 v[4:5], v[56:57], v[66:67] op_sel_hi:[1,0]
	v_pk_mul_f32 v[6:7], v[58:59], v[66:67] op_sel_hi:[1,0]
	v_cvt_pk_bf16_f32 v4, v4, v5
	v_cvt_pk_bf16_f32 v5, v6, v7
	v_mov_b32_e32 v76, v2
	v_mov_b32_e32 v77, v3
	v_mov_b32_e32 v84, v4
	v_mov_b32_e32 v85, v5
	v_lshlrev_b32_e32 v6, 16, v2
	v_and_b32_e32 v2, 0xffff0000, v2
	v_mul_f32_e32 v2, v2, v2
	v_fmac_f32_e32 v2, v6, v6
	v_lshlrev_b32_e32 v6, 16, v3
	v_and_b32_e32 v3, 0xffff0000, v3
	v_mul_f32_e32 v3, v3, v3
	v_fmac_f32_e32 v3, v6, v6
	v_add_f32_e32 v2, v2, v3
	v_lshlrev_b32_e32 v3, 16, v4
	v_and_b32_e32 v4, 0xffff0000, v4
	v_mul_f32_e32 v4, v4, v4
	v_fmac_f32_e32 v4, v3, v3
	v_add_f32_e32 v2, v4, v2
	v_and_b32_e32 v4, 0xffff0000, v5
	v_lshlrev_b32_e32 v3, 16, v5
	v_mul_f32_e32 v4, v4, v4
	v_fmac_f32_e32 v4, v3, v3
	v_add_f32_e32 v2, v4, v2
	v_add_f32_e32 v16, v2, v16
	v_pk_mul_f32 v[2:3], v[8:9], v[64:65] op_sel_hi:[1,0]
	v_pk_mul_f32 v[4:5], v[10:11], v[64:65] op_sel_hi:[1,0]
	v_cvt_pk_bf16_f32 v2, v2, v3
	v_cvt_pk_bf16_f32 v3, v4, v5
	v_pk_mul_f32 v[4:5], v[24:25], v[64:65] op_sel_hi:[1,0]
	v_pk_mul_f32 v[6:7], v[26:27], v[64:65] op_sel_hi:[1,0]
	v_cvt_pk_bf16_f32 v4, v4, v5
	v_cvt_pk_bf16_f32 v5, v6, v7
	v_mov_b32_e32 v92, v2
	v_mov_b32_e32 v93, v3
	v_mov_b32_e32 v100, v4
	v_mov_b32_e32 v101, v5
	v_lshlrev_b32_e32 v6, 16, v2
	v_and_b32_e32 v2, 0xffff0000, v2
	v_mul_f32_e32 v2, v2, v2
	v_fmac_f32_e32 v2, v6, v6
	v_lshlrev_b32_e32 v6, 16, v3
	v_and_b32_e32 v3, 0xffff0000, v3
	v_mul_f32_e32 v3, v3, v3
	v_fmac_f32_e32 v3, v6, v6
	v_add_f32_e32 v2, v2, v3
	v_lshlrev_b32_e32 v3, 16, v4
	v_and_b32_e32 v4, 0xffff0000, v4
	v_mul_f32_e32 v4, v4, v4
	v_fmac_f32_e32 v4, v3, v3
	v_add_f32_e32 v2, v4, v2
	v_and_b32_e32 v4, 0xffff0000, v5
	v_lshlrev_b32_e32 v3, 16, v5
	v_mul_f32_e32 v4, v4, v4
	v_fmac_f32_e32 v4, v3, v3
	v_add_f32_e32 v2, v4, v2
	v_add_f32_e32 v10, v2, v17
	v_pk_mul_f32 v[2:3], v[44:45], v[66:67] op_sel_hi:[1,0]
	v_pk_mul_f32 v[4:5], v[46:47], v[66:67] op_sel_hi:[1,0]
	v_cvt_pk_bf16_f32 v2, v2, v3
	v_cvt_pk_bf16_f32 v3, v4, v5
	v_pk_mul_f32 v[4:5], v[60:61], v[66:67] op_sel_hi:[1,0]
	v_pk_mul_f32 v[6:7], v[62:63], v[66:67] op_sel_hi:[1,0]
	v_cvt_pk_bf16_f32 v4, v4, v5
	v_cvt_pk_bf16_f32 v5, v6, v7
	v_mov_b32_e32 v78, v2
	v_mov_b32_e32 v79, v3
	v_mov_b32_e32 v86, v4
	v_mov_b32_e32 v87, v5
	v_lshlrev_b32_e32 v6, 16, v2
	v_and_b32_e32 v2, 0xffff0000, v2
	v_mul_f32_e32 v2, v2, v2
	v_fmac_f32_e32 v2, v6, v6
	v_lshlrev_b32_e32 v6, 16, v3
	v_and_b32_e32 v3, 0xffff0000, v3
	v_mul_f32_e32 v3, v3, v3
	v_fmac_f32_e32 v3, v6, v6
	v_add_f32_e32 v2, v2, v3
	v_lshlrev_b32_e32 v3, 16, v4
	v_and_b32_e32 v4, 0xffff0000, v4
	v_mul_f32_e32 v4, v4, v4
	v_fmac_f32_e32 v4, v3, v3
	v_add_f32_e32 v2, v4, v2
	v_and_b32_e32 v4, 0xffff0000, v5
	v_lshlrev_b32_e32 v3, 16, v5
	v_mul_f32_e32 v4, v4, v4
	v_fmac_f32_e32 v4, v3, v3
	v_add_f32_e32 v2, v4, v2
	v_pk_mul_f32 v[4:5], v[12:13], v[64:65] op_sel_hi:[1,0]
	v_pk_mul_f32 v[6:7], v[14:15], v[64:65] op_sel_hi:[1,0]
	v_cvt_pk_bf16_f32 v4, v4, v5
	v_cvt_pk_bf16_f32 v5, v6, v7
	v_pk_mul_f32 v[6:7], v[28:29], v[64:65] op_sel_hi:[1,0]
	v_pk_mul_f32 v[8:9], v[30:31], v[64:65] op_sel_hi:[1,0]
	v_cvt_pk_bf16_f32 v6, v6, v7
	v_cvt_pk_bf16_f32 v7, v8, v9
	v_mov_b32_e32 v94, v4
	v_mov_b32_e32 v95, v5
	v_mov_b32_e32 v102, v6
	v_mov_b32_e32 v103, v7
	v_mbcnt_lo_u32_b32 v108, -1, 0
	v_mbcnt_hi_u32_b32 v108, -1, v108
	v_and_b32_e32 v108, 32, v108
	v_lshrrev_b32_e32 v108, 2, v108
	v_mov_b32_e32 v109, 0
	v_lshl_add_u64 v[104:105], v[104:105], 0, v[108:109]
	v_lshl_add_u64 v[106:107], v[106:107], 0, v[108:109]
	s_nop 1
	v_permlane32_swap_b32_e32 v72, v74
	v_permlane32_swap_b32_e32 v73, v75
	v_permlane32_swap_b32_e32 v76, v78
	v_permlane32_swap_b32_e32 v77, v79
	v_permlane32_swap_b32_e32 v80, v82
	v_permlane32_swap_b32_e32 v81, v83
	v_permlane32_swap_b32_e32 v84, v86
	v_permlane32_swap_b32_e32 v85, v87
	v_permlane32_swap_b32_e32 v88, v90
	v_permlane32_swap_b32_e32 v89, v91
	v_permlane32_swap_b32_e32 v92, v94
	v_permlane32_swap_b32_e32 v93, v95
	v_permlane32_swap_b32_e32 v96, v98
	v_permlane32_swap_b32_e32 v97, v99
	v_permlane32_swap_b32_e32 v100, v102
	v_permlane32_swap_b32_e32 v101, v103
	global_store_dwordx4 v[104:105], v[72:75], off offset:2048
	global_store_dwordx4 v[104:105], v[76:79], off offset:2080
	global_store_dwordx4 v[104:105], v[80:83], off offset:2112
	global_store_dwordx4 v[104:105], v[84:87], off offset:2144
	global_store_dwordx4 v[106:107], v[88:91], off offset:2048
	global_store_dwordx4 v[106:107], v[92:95], off offset:2080
	global_store_dwordx4 v[106:107], v[96:99], off offset:2112
	global_store_dwordx4 v[106:107], v[100:103], off offset:2144
	v_and_b32_e32 v1, 0xffff0000, v4
	v_lshlrev_b32_e32 v0, 16, v4
	v_mul_f32_e32 v1, v1, v1
	v_and_b32_e32 v3, 0xffff0000, v5
	v_fmac_f32_e32 v1, v0, v0
	v_lshlrev_b32_e32 v0, 16, v5
	v_mul_f32_e32 v3, v3, v3
	v_fmac_f32_e32 v3, v0, v0
	v_add_f32_e32 v0, v1, v3
	v_and_b32_e32 v3, 0xffff0000, v6
	v_lshlrev_b32_e32 v1, 16, v6
	v_mul_f32_e32 v3, v3, v3
	v_fmac_f32_e32 v3, v1, v1
	v_add_f32_e32 v0, v3, v0
	v_and_b32_e32 v3, 0xffff0000, v7
	v_lshlrev_b32_e32 v1, 16, v7
	v_mul_f32_e32 v3, v3, v3
	v_fmac_f32_e32 v3, v1, v1
	v_add_f32_e32 v0, v3, v0
	v_add_f32_e32 v2, v2, v16
	v_add_f32_e32 v0, v0, v10
	ds_bpermute_b32 v1, v65, v2
	ds_bpermute_b32 v3, v65, v0
	v_cmp_eq_u32_e32 vcc, 0, v196
	s_and_saveexec_b64 s[12:13], vcc
	s_cbranch_execz .LBB0_206
	s_waitcnt lgkmcnt(1)
	v_add_f32_e32 v2, v2, v1
	v_mul_f32_e32 v2, 0x4b800000, v2
	v_trunc_f32_e32 v2, v2
	s_waitcnt lgkmcnt(0)
	v_add_f32_e32 v4, v0, v3
	v_mul_f32_e32 v3, 0x2f800000, v2
	v_floor_f32_e32 v3, v3
	v_fmac_f32_e32 v2, 0xcf800000, v3
	s_lshl_b32 s14, s54, 3
	v_cvt_u32_f32_e32 v2, v2
	v_cvt_u32_f32_e32 v3, v3
	s_add_u32 s14, s20, s14
	s_addc_u32 s15, s21, 0
	v_lshl_add_u64 v[0:1], v[182:183], 3, s[14:15]
	global_atomic_add_x2 v[0:1], v[2:3], off
	v_mul_f32_e32 v2, 0x4b800000, v4
	v_trunc_f32_e32 v2, v2
	v_mul_f32_e32 v3, 0x2f800000, v2
	v_floor_f32_e32 v3, v3
	v_fmac_f32_e32 v2, 0xcf800000, v3
	v_cvt_u32_f32_e32 v2, v2
	v_cvt_u32_f32_e32 v3, v3
	global_atomic_add_x2 v[0:1], v[2:3], off offset:256
	s_branch .LBB0_206
